# strategy 7.5: split packed fp32 mul/add into single ops in the attention tile loop (O rescale, s+sb)
# speedup vs baseline: 1.0042x; 1.0042x over previous
; #define LAS __attribute__((address_space(3)))
; __device__ __forceinline__ void attn_wave_unit(LAS unsigned char* wl, const bf16* __restrict__ Q, const bf16* __restrict__ Kb, const bf16* __restrict__ V, const float* ssq_x, const float* ssq_qk, ...
;     ...
;         f32x16 s, sb;
; #pragma unroll
;         for (int e = 0; e < 16; ++e) { s[e] = 0.f; sb[e] = 0.f; }
; #pragma unroll
;         for (int ks = 0; ks < 8; ks += 2) {
;             const bf16x8 k0 = *(const LAS bf16x8*)(wl + kfbase + 32 * ks), k1 = *(const LAS bf16x8*)(wl + kfbase + 32 * ks + 32);
;             s = __builtin_amdgcn_mfma_f32_32x32x16_bf16(k0, qf[ks], s, 0, 0, 0); sb = __builtin_amdgcn_mfma_f32_32x32x16_bf16(k1, qf[ks + 1], sb, 0, 0, 0); }
;         s = s + sb;
;         float mt = -INFINITY;
; #pragma unroll
;         for (int g4 = 0; g4 < 4; ++g4) { const f32x4 ck4 = *(const LAS f32x4*)(ckl + 32 * t + 8 * g4 + 4 * hh);
; #pragma unroll
;             for (int j = 0; j < 4; ++j) { const int rr = 4 * g4 + j; const int ka = kb + 8 * g4 + 4 * hh + j; const int df = ka - qa;
;                 const bool ok = ((unsigned)ka < (unsigned)L) & ((unsigned)(df + 64) <= 128u);
;                 const float v = s[rr] * (cq * ck4[j]); const float sc = ok ? v : -INFINITY; s[rr] = sc; mt = fmaxf(mt, sc); } }
;         mt = fmaxf(mt, __shfl_xor(mt, 32));
.LBB0_523:
	s_waitcnt lgkmcnt(0)
	v_add_u32_e32 v247, v231, v230
	ds_read_b128 v[64:67], v247 offset:10240
	ds_read_b128 v[80:83], v247 offset:10272
	ds_read_b128 v[248:251], v247 offset:10304
	ds_read_b128 v[196:199], v247 offset:10336
	s_mov_b32 s41, 0xff800000
	s_waitcnt lgkmcnt(0)
	v_mfma_f32_32x32x16_bf16 v[64:79], v[64:67], v[98:101], 0
	v_mfma_f32_32x32x16_bf16 v[80:95], v[80:83], v[102:105], 0
	v_mfma_f32_32x32x16_bf16 v[64:79], v[248:251], v[106:109], v[64:79]
	v_mfma_f32_32x32x16_bf16 v[80:95], v[196:199], v[110:113], v[80:95]
	ds_read_b128 v[196:199], v247 offset:10368
	ds_read_b128 v[248:251], v247 offset:10400
	s_waitcnt lgkmcnt(0)
	v_mfma_f32_32x32x16_bf16 v[64:79], v[196:199], v[114:117], v[64:79]
	v_mfma_f32_32x32x16_bf16 v[80:95], v[248:251], v[118:121], v[80:95]
	ds_read_b128 v[196:199], v247 offset:10432
	ds_read_b128 v[248:251], v247 offset:10464
	s_waitcnt lgkmcnt(0)
	v_mfma_f32_32x32x16_bf16 v[64:79], v[196:199], v[122:125], v[64:79]
	v_mfma_f32_32x32x16_bf16 v[80:95], v[248:251], v[126:129], v[80:95]
	s_nop 11
	v_add_f32_e32 v82, v66, v82
	v_add_f32_e32 v83, v67, v83
	v_add_f32_e32 v80, v64, v80
	v_add_f32_e32 v81, v65, v81
	ds_read_b128 v[64:67], v244
	v_add_f32_e32 v72, v72, v88
	v_add_f32_e32 v73, v73, v89
	v_add_u32_e32 v88, s40, v243
	v_add_f32_e32 v84, v68, v84
	v_add_f32_e32 v85, v69, v85
	v_subrev_u32_e32 v68, 64, v88
	v_cmp_gt_u32_e32 vcc, s93, v68
	v_sub_u32_e32 v68, v203, v227
	v_add_u32_e32 v89, s40, v68
	v_add_f32_e32 v86, v70, v86
	v_add_f32_e32 v87, v71, v87
	v_cmp_gt_u32_e64 s[60:61], s4, v89
	ds_read_b128 v[68:71], v244 offset:32
	s_waitcnt lgkmcnt(0)
	v_mul_f32_e32 v64, v242, v64
	v_mul_f32_e32 v64, v80, v64
	s_and_b64 vcc, vcc, s[60:61]
	v_cndmask_b32_e32 v80, v222, v64, vcc
	v_subrev_u32_e32 v64, 63, v88
	v_cmp_gt_u32_e32 vcc, s93, v64
	v_add_u32_e32 v64, 1, v89
	v_cmp_gt_u32_e64 s[60:61], s4, v64
	v_mul_f32_e32 v64, v242, v65
	v_mul_f32_e32 v64, v81, v64
	s_and_b64 vcc, vcc, s[60:61]
	v_subrev_u32_e32 v65, 62, v88
	v_cndmask_b32_e32 v81, v222, v64, vcc
	v_cmp_gt_u32_e32 vcc, s93, v65
	v_add_u32_e32 v65, 2, v89
	v_cmp_gt_u32_e64 s[60:61], s4, v65
	v_mul_f32_e32 v65, v242, v66
	v_mul_f32_e32 v65, v82, v65
	s_and_b64 vcc, vcc, s[60:61]
	v_cndmask_b32_e32 v82, v222, v65, vcc
	v_subrev_u32_e32 v65, 61, v88
	v_cmp_gt_u32_e32 vcc, s93, v65
	v_add_u32_e32 v65, 3, v89
	v_cmp_gt_u32_e64 s[60:61], s4, v65
	v_mul_f32_e32 v65, v242, v67
	v_mul_f32_e32 v65, v83, v65
	s_and_b64 vcc, vcc, s[60:61]
	v_cndmask_b32_e32 v83, v222, v65, vcc
	v_subrev_u32_e32 v65, 56, v88
	v_cmp_gt_u32_e32 vcc, s93, v65
	v_add_u32_e32 v65, 8, v89
	v_cmp_gt_u32_e64 s[60:61], s4, v65
	v_mul_f32_e32 v65, v242, v68
	v_mul_f32_e32 v65, v84, v65
	s_and_b64 vcc, vcc, s[60:61]
	v_cndmask_b32_e32 v84, v222, v65, vcc
	v_subrev_u32_e32 v65, 55, v88
	v_cmp_gt_u32_e32 vcc, s93, v65
	v_add_u32_e32 v65, 9, v89
	v_cmp_gt_u32_e64 s[60:61], s4, v65
	v_mul_f32_e32 v65, v242, v69
	v_mul_f32_e32 v65, v85, v65
	s_and_b64 vcc, vcc, s[60:61]
	v_cndmask_b32_e32 v85, v222, v65, vcc
	v_subrev_u32_e32 v65, 54, v88
	v_cmp_gt_u32_e32 vcc, s93, v65
	v_add_u32_e32 v65, 10, v89
	v_cmp_gt_u32_e64 s[60:61], s4, v65
	v_mul_f32_e32 v65, v242, v70
	v_mul_f32_e32 v65, v86, v65
	s_and_b64 vcc, vcc, s[60:61]
	v_cndmask_b32_e32 v86, v222, v65, vcc
	v_subrev_u32_e32 v65, 53, v88
	v_cmp_gt_u32_e32 vcc, s93, v65
	v_add_u32_e32 v65, 11, v89
	v_max3_f32 v64, v80, s41, v81
	v_cmp_gt_u32_e64 s[60:61], s4, v65
	v_mul_f32_e32 v65, v242, v71
	v_max3_f32 v64, v64, v82, v83
	v_mul_f32_e32 v65, v87, v65
	s_and_b64 vcc, vcc, s[60:61]
	v_max3_f32 v64, v64, v84, v85
	v_cndmask_b32_e32 v87, v222, v65, vcc
	v_add_f32_e32 v74, v74, v90
	v_add_f32_e32 v75, v75, v91
	v_max3_f32 v90, v64, v86, v87
	ds_read_b128 v[64:67], v244 offset:64
	v_subrev_u32_e32 v68, 48, v88
	v_cmp_gt_u32_e32 vcc, s93, v68
	v_add_u32_e32 v68, 16, v89
	v_cmp_gt_u32_e64 s[60:61], s4, v68
	ds_read_b128 v[68:71], v244 offset:96
	s_waitcnt lgkmcnt(0)
	v_mul_f32_e32 v64, v242, v64
	v_mul_f32_e32 v64, v72, v64
	s_and_b64 vcc, vcc, s[60:61]
	v_cndmask_b32_e32 v72, v222, v64, vcc
	v_subrev_u32_e32 v64, 47, v88
	v_cmp_gt_u32_e32 vcc, s93, v64
	v_add_u32_e32 v64, 17, v89
	v_cmp_gt_u32_e64 s[60:61], s4, v64
	v_mul_f32_e32 v64, v242, v65
	v_mul_f32_e32 v64, v73, v64
	s_and_b64 vcc, vcc, s[60:61]
	v_subrev_u32_e32 v65, 46, v88
	v_cndmask_b32_e32 v73, v222, v64, vcc
	v_cmp_gt_u32_e32 vcc, s93, v65
	v_add_u32_e32 v65, 18, v89
	v_cmp_gt_u32_e64 s[60:61], s4, v65
	v_mul_f32_e32 v65, v242, v66
	v_mul_f32_e32 v65, v74, v65
	s_and_b64 vcc, vcc, s[60:61]
	v_cndmask_b32_e32 v66, v222, v65, vcc
	v_subrev_u32_e32 v65, 45, v88
	v_cmp_gt_u32_e32 vcc, s93, v65
	v_add_u32_e32 v65, 19, v89
	v_cmp_gt_u32_e64 s[60:61], s4, v65
	v_mul_f32_e32 v65, v242, v67
	v_mul_f32_e32 v65, v75, v65
	s_and_b64 vcc, vcc, s[60:61]
	v_cndmask_b32_e32 v67, v222, v65, vcc
	v_subrev_u32_e32 v65, 40, v88
	v_cmp_gt_u32_e32 vcc, s93, v65
	v_add_u32_e32 v65, 24, v89
	v_add_f32_e32 v76, v76, v92
	v_add_f32_e32 v77, v77, v93
	v_cmp_gt_u32_e64 s[60:61], s4, v65
	v_mul_f32_e32 v65, v242, v68
	v_mul_f32_e32 v65, v76, v65
	s_and_b64 vcc, vcc, s[60:61]
	v_cndmask_b32_e32 v68, v222, v65, vcc
	v_subrev_u32_e32 v65, 39, v88
	v_cmp_gt_u32_e32 vcc, s93, v65
	v_add_u32_e32 v65, 25, v89
	v_cmp_gt_u32_e64 s[60:61], s4, v65
	v_mul_f32_e32 v65, v242, v69
	v_mul_f32_e32 v65, v77, v65
	s_and_b64 vcc, vcc, s[60:61]
	v_cndmask_b32_e32 v69, v222, v65, vcc
	v_subrev_u32_e32 v65, 38, v88
	v_cmp_gt_u32_e32 vcc, s93, v65
	v_add_u32_e32 v65, 26, v89
	v_add_f32_e32 v78, v78, v94
	v_add_f32_e32 v79, v79, v95
	v_cmp_gt_u32_e64 s[60:61], s4, v65
	v_mul_f32_e32 v65, v242, v70
	v_mul_f32_e32 v65, v78, v65
	s_and_b64 vcc, vcc, s[60:61]
	v_cndmask_b32_e32 v70, v222, v65, vcc
	v_subrev_u32_e32 v65, 37, v88
	v_cmp_gt_u32_e32 vcc, s93, v65
	v_add_u32_e32 v65, 27, v89
	v_max3_f32 v64, v90, v72, v73
	v_cmp_gt_u32_e64 s[60:61], s4, v65
	v_mul_f32_e32 v65, v242, v71
	v_max3_f32 v64, v64, v66, v67
	v_mul_f32_e32 v65, v79, v65
	s_and_b64 vcc, vcc, s[60:61]
	v_max3_f32 v64, v64, v68, v69
	v_cndmask_b32_e32 v71, v222, v65, vcc
	v_max3_f32 v64, v64, v70, v71
	ds_bpermute_b32 v65, v219, v64
	s_add_i32 s40, s40, 32
	s_cmpk_eq_i32 s40, 0xa0
	v_add_u32_e32 v244, 0x80, v244
	s_waitcnt lgkmcnt(0)
; __device__ __forceinline__ unsigned cvt_pk_bf16(float lo, float hi) { unsigned r; asm volatile("v_cvt_pk_bf16_f32 %0, %1, %2" : "=v"(r) : "v"(lo), "v"(hi)); return r; }
; #define LAS __attribute__((address_space(3)))
; __device__ __forceinline__ void attn_wave_unit(LAS unsigned char* wl, const bf16* __restrict__ Q, const bf16* __restrict__ Kb, const bf16* __restrict__ V, const float* ssq_x, const float* ssq_qk, ...
;     ...
;         mt = fmaxf(mt, __shfl_xor(mt, 32));
;         const float mn = fmaxf(m_run, mt); const float alpha = __builtin_amdgcn_exp2f(m_run - mn); m_run = mn;
;         float ps = 0.f;
; #pragma unroll
;         for (int e = 0; e < 16; ++e) { const float pe = __builtin_amdgcn_exp2f(s[e] - mn); s[e] = pe; ps += pe; }
;         l_run = l_run * alpha + ps;
; #pragma unroll
;         for (int db = 0; db < 4; ++db)
; #pragma unroll
;             for (int e = 0; e < 16; ++e) o[db][e] *= alpha;
;         bf16x8 pf[2];
; #pragma unroll
;         for (int s2 = 0; s2 < 2; ++s2) { u32x4 w; w.x = pg8::cvt_pk_bf16(s[8 * s2 + 0], s[8 * s2 + 1]); w.y = pg8::cvt_pk_bf16(s[8 * s2 + 2], s[8 * s2 + 3]);
;             w.z = pg8::cvt_pk_bf16(s[8 * s2 + 4], s[8 * s2 + 5]); w.w = pg8::cvt_pk_bf16(s[8 * s2 + 6], s[8 * s2 + 7]); pf[s2] = __builtin_bit_cast(bf16x8, w); }
;         bf16x8 vf[2][4];
; #pragma unroll
;         for (int s2 = 0; s2 < 2; ++s2)
; #pragma unroll
;             for (int db = 0; db < 4; ++db) {
;                 const s16x4 lo = __builtin_bit_cast(s16x4, __builtin_amdgcn_ds_read_tr16_b64_v4i16((LAS s16x4*)(wl + trbase + (16 * s2) * VPITCH + db * 64)));
;                 const s16x4 hi = __builtin_bit_cast(s16x4, __builtin_amdgcn_ds_read_tr16_b64_v4i16((LAS s16x4*)(wl + trbase + (16 * s2 + 8) * VPITCH + db * 64)));
;                 vf[s2][db] = __builtin_shufflevector(lo, hi, 0, 1, 2, 3, 4, 5, 6, 7); }
; #pragma unroll
;         for (int s2 = 0; s2 < 2; ++s2)
; #pragma unroll
;             for (int db = 0; db < 4; ++db) o[db] = __builtin_amdgcn_mfma_f32_32x32x16_bf16(vf[s2][db], pf[s2], o[db], 0, 0, 0);
;         asm volatile("s_waitcnt lgkmcnt(0)" ::: "memory");
	v_max3_f32 v65, v246, v64, v65
	v_sub_f32_e32 v74, v80, v65
	v_exp_f32_e32 v90, v74
	v_sub_f32_e32 v74, v81, v65
	v_exp_f32_e32 v91, v74
	v_sub_f32_e32 v74, v82, v65
	v_sub_f32_e32 v66, v66, v65
	v_sub_f32_e32 v64, v246, v65
	v_exp_f32_e32 v92, v74
	v_sub_f32_e32 v74, v83, v65
	v_exp_f32_e32 v246, v66
	v_sub_f32_e32 v66, v67, v65
	v_exp_f32_e32 v93, v74
	v_sub_f32_e32 v74, v84, v65
	v_exp_f32_e32 v247, v66
	v_sub_f32_e32 v66, v68, v65
	v_exp_f32_e32 v94, v74
	v_sub_f32_e32 v74, v85, v65
	v_exp_f32_e32 v248, v66
	v_sub_f32_e32 v66, v69, v65
	v_exp_f32_e32 v95, v74
	v_sub_f32_e32 v74, v86, v65
	v_sub_f32_e32 v72, v72, v65
	v_exp_f32_e32 v249, v66
	v_sub_f32_e32 v66, v70, v65
	v_exp_f32_e32 v196, v74
	v_sub_f32_e32 v74, v87, v65
	v_exp_f32_e32 v198, v72
	v_sub_f32_e32 v72, v73, v65
	v_exp_f32_e32 v250, v66
	v_sub_f32_e32 v66, v71, v65
	v_exp_f32_e32 v64, v64
	v_exp_f32_e32 v197, v74
	v_exp_f32_e32 v199, v72
	v_exp_f32_e32 v251, v66
	v_cvt_pk_bf16_f32 v66, v90, v91
	v_cvt_pk_bf16_f32 v67, v92, v93
	v_cvt_pk_bf16_f32 v68, v94, v95
	v_cvt_pk_bf16_f32 v69, v196, v197
	v_cvt_pk_bf16_f32 v70, v198, v199
	v_cvt_pk_bf16_f32 v71, v246, v247
	v_cvt_pk_bf16_f32 v72, v248, v249
	v_cvt_pk_bf16_f32 v73, v250, v251
	ds_read_b64_tr_b16 v[74:75], v237
	ds_read_b64_tr_b16 v[76:77], v237 offset:2560
	v_mul_f32_e32 v62, v64, v62
	v_mul_f32_e32 v63, v64, v63
	v_mul_f32_e32 v60, v64, v60
	v_mul_f32_e32 v61, v64, v61
	v_mul_f32_e32 v58, v64, v58
	v_mul_f32_e32 v59, v64, v59
	v_mul_f32_e32 v56, v64, v56
	v_mul_f32_e32 v57, v64, v57
	v_mul_f32_e32 v54, v64, v54
	v_mul_f32_e32 v55, v64, v55
	v_mul_f32_e32 v52, v64, v52
	v_mul_f32_e32 v53, v64, v53
	v_mul_f32_e32 v50, v64, v50
	v_mul_f32_e32 v51, v64, v51
	v_mul_f32_e32 v48, v64, v48
	v_mul_f32_e32 v49, v64, v49
	ds_read_b64_tr_b16 v[78:79], v237 offset:64
	ds_read_b64_tr_b16 v[82:83], v237 offset:128
	ds_read_b64_tr_b16 v[86:87], v237 offset:192
	ds_read_b64_tr_b16 v[80:81], v237 offset:2624
	ds_read_b64_tr_b16 v[84:85], v237 offset:2688
	ds_read_b64_tr_b16 v[88:89], v237 offset:2752
	s_waitcnt lgkmcnt(0)
	v_mfma_f32_32x32x16_bf16 v[48:63], v[74:77], v[66:69], v[48:63]
	ds_read_b64_tr_b16 v[76:77], v237 offset:7680
	v_mul_f32_e64 v46, v46, v64
	v_mul_f32_e64 v47, v47, v64
	v_mul_f32_e64 v44, v44, v64
	v_mul_f32_e64 v45, v45, v64
	v_mul_f32_e32 v42, v64, v42
	v_mul_f32_e32 v43, v64, v43
	v_mul_f32_e32 v40, v64, v40
	v_mul_f32_e32 v41, v64, v41
	v_mul_f32_e32 v38, v64, v38
	v_mul_f32_e32 v39, v64, v39
	v_mul_f32_e32 v36, v64, v36
	v_mul_f32_e32 v37, v64, v37
	v_mul_f32_e32 v34, v64, v34
	v_mul_f32_e32 v35, v64, v35
	v_mul_f32_e32 v32, v64, v32
	v_mul_f32_e32 v33, v64, v33
	v_mul_f32_e32 v30, v64, v30
	v_mul_f32_e32 v31, v64, v31
	v_mul_f32_e32 v28, v64, v28
	v_mul_f32_e32 v29, v64, v29
	v_mfma_f32_32x32x16_bf16 v[32:47], v[78:81], v[66:69], v[32:47]
	v_mul_f32_e64 v26, v26, v64
	v_mul_f32_e64 v27, v27, v64
	v_mul_f32_e64 v24, v24, v64
	v_mul_f32_e64 v25, v25, v64
	v_mul_f32_e64 v22, v22, v64
	v_mul_f32_e64 v23, v23, v64
	v_mul_f32_e32 v20, v64, v20
	v_mul_f32_e32 v21, v64, v21
	v_mul_f32_e32 v18, v64, v18
	v_mul_f32_e32 v19, v64, v19
	v_mul_f32_e32 v16, v64, v16
	v_mul_f32_e32 v17, v64, v17
	v_mul_f32_e32 v14, v64, v14
	v_mul_f32_e32 v15, v64, v15
	v_mul_f32_e32 v12, v64, v12
	v_mul_f32_e32 v13, v64, v13
	v_mul_f32_e32 v10, v64, v10
	v_mul_f32_e32 v11, v64, v11
	v_mul_f32_e32 v8, v64, v8
	v_mul_f32_e32 v9, v64, v9
	v_mul_f32_e32 v6, v64, v6
	v_mul_f32_e32 v7, v64, v7
	v_mul_f32_e32 v4, v64, v4
	v_mul_f32_e32 v5, v64, v5
	v_mul_f32_e32 v2, v64, v2
	v_mul_f32_e32 v3, v64, v3
	v_mul_f32_e32 v0, v64, v0
	v_mul_f32_e32 v1, v64, v1
	v_mfma_f32_32x32x16_bf16 v[16:31], v[82:85], v[66:69], v[16:31]
	s_nop 0
	v_mfma_f32_32x32x16_bf16 v[0:15], v[86:89], v[66:69], v[0:15]
	ds_read_b64_tr_b16 v[74:75], v237 offset:5120
	ds_read_b64_tr_b16 v[66:67], v237 offset:5184
	ds_read_b64_tr_b16 v[78:79], v237 offset:5248
	ds_read_b64_tr_b16 v[82:83], v237 offset:5312
	ds_read_b64_tr_b16 v[68:69], v237 offset:7744
	ds_read_b64_tr_b16 v[80:81], v237 offset:7808
	ds_read_b64_tr_b16 v[84:85], v237 offset:7872
	s_waitcnt lgkmcnt(0)
	s_waitcnt lgkmcnt(0)
	v_mfma_f32_32x32x16_bf16 v[48:63], v[74:77], v[70:73], v[48:63]
	v_add_f32_e32 v74, 0, v90
	v_add_f32_e32 v74, v91, v74
	v_mfma_f32_32x32x16_bf16 v[32:47], v[66:69], v[70:73], v[32:47]
	v_add_f32_e32 v66, v92, v74
	v_add_f32_e32 v66, v93, v66
	v_add_f32_e32 v66, v94, v66
	v_add_f32_e32 v66, v95, v66
	v_add_f32_e32 v66, v196, v66
	v_add_f32_e32 v66, v197, v66
	v_add_f32_e32 v66, v198, v66
	v_mfma_f32_32x32x16_bf16 v[16:31], v[78:81], v[70:73], v[16:31]
	v_add_f32_e32 v66, v199, v66
	v_add_f32_e32 v66, v246, v66
	v_add_f32_e32 v66, v247, v66
	v_add_f32_e32 v66, v248, v66
	v_add_f32_e32 v66, v249, v66
	v_add_f32_e32 v66, v250, v66
	v_add_f32_e32 v66, v251, v66
	v_mfma_f32_32x32x16_bf16 v[0:15], v[82:85], v[70:73], v[0:15]
	v_fmac_f32_e32 v66, v245, v64
	s_cbranch_scc1 .LBB0_525
	v_mov_b32_e32 v245, v66
	v_mov_b32_e32 v246, v65
	s_branch .LBB0_521
